# phase-0 x and layer-0 weight f32 loads non-temporal
# speedup vs baseline: 1.0136x; 1.0069x over previous
; __device__ __forceinline__ void transpose_item(const float* W, int K, int N, bf16* WT, const float* scale, LAS float* scr, int item, int lane) {
;     const int nblk = N / 32, kb = item / nblk, nb = item % nblk, k0 = 64 * kb, n0 = 32 * nb;
;     {
;         const int q = lane & 7, r = lane >> 3;
;         f32x4 v[8];
; #pragma unroll
;         for (int i = 0; i < 8; ++i) v[i] = *(const f32x4*)(W + (size_t)(k0 + 8 * i + r) * N + n0 + 4 * q);
; #pragma unroll
;         for (int i = 0; i < 8; ++i) { const int kk = 8 * i + r; f32x4 x = v[i]; if (scale) x = x * scale[k0 + kk];
;             scr[kk * 33 + 4 * q + 0] = x[0]; scr[kk * 33 + 4 * q + 1] = x[1]; scr[kk * 33 + 4 * q + 2] = x[2]; scr[kk * 33 + 4 * q + 3] = x[3]; }
.LBB0_9:
	s_ashr_i32 s10, s16, 31
	s_lshr_b32 s10, s10, 25
	s_add_i32 s10, s16, s10
	s_ashr_i32 s11, s10, 7
	s_lshl_b32 s10, s11, 6
	s_lshl_b32 s17, s11, 12
	v_or_b32_e32 v34, s10, v38
	s_sub_i32 s12, s14, s17
	v_or_b32_e32 v6, 8, v34
	s_ashr_i32 s13, s12, 31
	v_ashrrev_i32_e32 v35, 31, v34
	v_ashrrev_i32_e32 v7, 31, v6
	v_lshl_add_u64 v[2:3], s[12:13], 2, v[40:41]
	v_lshlrev_b64 v[4:5], 14, v[34:35]
	v_lshlrev_b64 v[6:7], 14, v[6:7]
	v_lshl_add_u64 v[4:5], v[2:3], 0, v[4:5]
	v_lshl_add_u64 v[6:7], v[2:3], 0, v[6:7]
	global_load_dwordx4 v[26:29], v[4:5], off nt
	global_load_dwordx4 v[30:33], v[6:7], off nt
	v_or_b32_e32 v4, 16, v34
	v_or_b32_e32 v6, 24, v34
	v_ashrrev_i32_e32 v5, 31, v4
	v_ashrrev_i32_e32 v7, 31, v6
	v_lshlrev_b64 v[4:5], 14, v[4:5]
	v_lshlrev_b64 v[6:7], 14, v[6:7]
	v_lshl_add_u64 v[4:5], v[2:3], 0, v[4:5]
	v_lshl_add_u64 v[6:7], v[2:3], 0, v[6:7]
	global_load_dwordx4 v[18:21], v[4:5], off nt
	global_load_dwordx4 v[22:25], v[6:7], off nt
	v_or_b32_e32 v4, 32, v34
	v_or_b32_e32 v6, 40, v34
	v_ashrrev_i32_e32 v5, 31, v4
	v_ashrrev_i32_e32 v7, 31, v6
	v_lshlrev_b64 v[4:5], 14, v[4:5]
	v_lshlrev_b64 v[6:7], 14, v[6:7]
	v_lshl_add_u64 v[4:5], v[2:3], 0, v[4:5]
	v_lshl_add_u64 v[6:7], v[2:3], 0, v[6:7]
	global_load_dwordx4 v[10:13], v[4:5], off nt
	global_load_dwordx4 v[14:17], v[6:7], off nt
	v_or_b32_e32 v4, 48, v34
	v_or_b32_e32 v6, 56, v34
	v_ashrrev_i32_e32 v5, 31, v4
	v_ashrrev_i32_e32 v7, 31, v6
	v_lshlrev_b64 v[4:5], 14, v[4:5]
	v_lshlrev_b64 v[6:7], 14, v[6:7]
	v_lshl_add_u64 v[4:5], v[2:3], 0, v[4:5]
	v_lshl_add_u64 v[6:7], v[2:3], 0, v[6:7]
	global_load_dwordx4 v[2:5], v[4:5], off nt
	s_nop 0
	global_load_dwordx4 v[6:9], v[6:7], off nt
	s_and_b64 vcc, exec, s[4:5]
	s_cbranch_vccnz .LBB0_20
	s_ashr_i32 s11, s10, 31
	v_lshl_add_u64 v[36:37], s[10:11], 0, v[38:39]
	v_lshl_add_u64 v[34:35], v[34:35], 2, s[58:59]
	v_lshl_add_u64 v[36:37], v[36:37], 2, s[58:59]
	global_load_dword v34, v[34:35], off
	s_nop 0
	global_load_dword v50, v[36:37], off offset:32
	s_waitcnt vmcnt(1)
	v_pk_mul_f32 v[44:45], v[28:29], v[34:35] op_sel_hi:[1,0]
	v_pk_mul_f32 v[46:47], v[26:27], v[34:35] op_sel_hi:[1,0]
	s_waitcnt vmcnt(0)
	v_pk_mul_f32 v[36:37], v[32:33], v[50:51] op_sel_hi:[1,0]
	v_pk_mul_f32 v[34:35], v[30:31], v[50:51] op_sel_hi:[1,0]
	s_cbranch_execnz .LBB0_12

; #define LAS __attribute__((address_space(3)))
; __device__ __forceinline__ unsigned pk2(float lo, float hi) { f32x2_t v = {lo, hi}; bf16x2_t b = __builtin_convertvector(v, bf16x2_t); return __builtin_bit_cast(unsigned, b); }
; __device__ __forceinline__ void transpose_item(const float* W, int K, int N, bf16* WT, const float* scale, LAS float* scr, int item, int lane) {
;     const int nblk = N / 32, kb = item / nblk, nb = item % nblk, k0 = 64 * kb, n0 = 32 * nb;
;     {
;         const int q = lane & 7, r = lane >> 3;
;         f32x4 v[8];
; #pragma unroll
;         for (int i = 0; i < 8; ++i) v[i] = *(const f32x4*)(W + (size_t)(k0 + 8 * i + r) * N + n0 + 4 * q);
; #pragma unroll
;         for (int i = 0; i < 8; ++i) { const int kk = 8 * i + r; f32x4 x = v[i]; if (scale) x = x * scale[k0 + kk];
;             scr[kk * 33 + 4 * q + 0] = x[0]; scr[kk * 33 + 4 * q + 1] = x[1]; scr[kk * 33 + 4 * q + 2] = x[2]; scr[kk * 33 + 4 * q + 3] = x[3]; }
;     }
;     asm volatile("s_waitcnt lgkmcnt(0)" ::: "memory");
;     const int c = lane & 7;
; #pragma unroll
;     for (int j = 0; j < 4; ++j) { const int n = (lane >> 3) + 8 * j; const LAS float* s = scr + (8 * c) * 33 + n;
;         v4u o; o.x = pk2(s[0 * 33], s[1 * 33]); o.y = pk2(s[2 * 33], s[3 * 33]); o.z = pk2(s[4 * 33], s[5 * 33]); o.w = pk2(s[6 * 33], s[7 * 33]);
;         *(v4u*)(WT + (size_t)(n0 + n) * K + k0 + 8 * c) = o; }
;     asm volatile("s_waitcnt lgkmcnt(0)" ::: "memory");
.LBB0_27:
	s_ashr_i32 s4, s14, 31
	s_lshr_b32 s4, s4, 27
	s_add_i32 s4, s14, s4
	s_ashr_i32 s5, s4, 5
	s_lshl_b32 s4, s5, 6
	s_lshl_b32 s5, s5, 10
	v_or_b32_e32 v22, s4, v1
	s_sub_i32 s10, s12, s5
	v_or_b32_e32 v24, 8, v22
	s_ashr_i32 s11, s10, 31
	v_ashrrev_i32_e32 v23, 31, v22
	v_or_b32_e32 v26, 16, v22
	v_or_b32_e32 v28, 24, v22
	v_or_b32_e32 v30, 32, v22
	v_or_b32_e32 v32, 40, v22
	v_or_b32_e32 v34, 48, v22
	v_or_b32_e32 v36, 56, v22
	v_ashrrev_i32_e32 v25, 31, v24
	v_lshl_add_u64 v[38:39], s[10:11], 2, v[2:3]
	v_lshlrev_b64 v[22:23], 12, v[22:23]
	v_ashrrev_i32_e32 v27, 31, v26
	v_ashrrev_i32_e32 v29, 31, v28
	v_ashrrev_i32_e32 v31, 31, v30
	v_ashrrev_i32_e32 v33, 31, v32
	v_ashrrev_i32_e32 v35, 31, v34
	v_ashrrev_i32_e32 v37, 31, v36
	v_lshlrev_b64 v[40:41], 12, v[24:25]
	v_lshl_add_u64 v[22:23], v[38:39], 0, v[22:23]
	v_lshlrev_b64 v[26:27], 12, v[26:27]
	v_lshlrev_b64 v[28:29], 12, v[28:29]
	v_lshlrev_b64 v[30:31], 12, v[30:31]
	v_lshlrev_b64 v[32:33], 12, v[32:33]
	v_lshlrev_b64 v[34:35], 12, v[34:35]
	v_lshlrev_b64 v[36:37], 12, v[36:37]
	v_lshl_add_u64 v[54:55], v[38:39], 0, v[40:41]
	global_load_dwordx4 v[22:25], v[22:23], off nt
	v_lshl_add_u64 v[56:57], v[38:39], 0, v[26:27]
	v_lshl_add_u64 v[58:59], v[38:39], 0, v[28:29]
	v_lshl_add_u64 v[60:61], v[38:39], 0, v[30:31]
	v_lshl_add_u64 v[62:63], v[38:39], 0, v[32:33]
	v_lshl_add_u64 v[64:65], v[38:39], 0, v[34:35]
	v_lshl_add_u64 v[66:67], v[38:39], 0, v[36:37]
	global_load_dwordx4 v[26:29], v[54:55], off nt
	global_load_dwordx4 v[30:33], v[56:57], off nt
	global_load_dwordx4 v[34:37], v[58:59], off nt
	global_load_dwordx4 v[38:41], v[60:61], off nt
	global_load_dwordx4 v[42:45], v[62:63], off nt
	global_load_dwordx4 v[46:49], v[64:65], off nt
	global_load_dwordx4 v[50:53], v[66:67], off nt
	v_add_u32_e32 v56, s10, v1
	v_add_u32_e32 v58, 8, v56
	v_add_u32_e32 v60, 16, v56
	v_add_u32_e32 v62, 24, v56
	s_ashr_i32 s5, s4, 31
	v_ashrrev_i32_e32 v57, 31, v56
	v_ashrrev_i32_e32 v59, 31, v58
	v_ashrrev_i32_e32 v61, 31, v60
	v_ashrrev_i32_e32 v63, 31, v62
	v_lshl_add_u64 v[54:55], s[4:5], 1, v[4:5]
	v_lshlrev_b64 v[56:57], 11, v[56:57]
	v_lshlrev_b64 v[58:59], 11, v[58:59]
	v_lshlrev_b64 v[60:61], 11, v[60:61]
	v_lshlrev_b64 v[62:63], 11, v[62:63]
	v_lshl_add_u64 v[56:57], v[54:55], 0, v[56:57]
	v_lshl_add_u64 v[58:59], v[54:55], 0, v[58:59]
	v_lshl_add_u64 v[60:61], v[54:55], 0, v[60:61]
	v_lshl_add_u64 v[54:55], v[54:55], 0, v[62:63]
	s_add_i32 s14, s14, s28
	s_add_i32 s12, s12, s13
	s_cmpk_lt_i32 s14, 0x200
	s_waitcnt vmcnt(7)
	ds_write2_b32 v7, v22, v23 offset1:1
	ds_write2_b32 v7, v24, v25 offset0:2 offset1:3
	s_waitcnt vmcnt(6)
	ds_write2_b32 v8, v26, v27 offset1:1
	ds_write2_b32 v9, v28, v29 offset1:1
	s_waitcnt vmcnt(5)
	ds_write2_b32 v10, v30, v31 offset1:1
	ds_write2_b32 v11, v32, v33 offset1:1
	s_waitcnt vmcnt(4)
	ds_write2_b32 v12, v34, v35 offset1:1
	ds_write2_b32 v13, v36, v37 offset1:1
	s_waitcnt vmcnt(3)
	ds_write2_b32 v14, v38, v39 offset1:1
	ds_write2_b32 v15, v40, v41 offset1:1
	s_waitcnt vmcnt(2)
	ds_write2_b32 v16, v42, v43 offset1:1
	ds_write2_b32 v17, v44, v45 offset1:1
	s_waitcnt vmcnt(1)
	ds_write2_b32 v18, v46, v47 offset1:1
	ds_write2_b32 v19, v48, v49 offset1:1
	s_waitcnt vmcnt(0)
	ds_write2_b32 v20, v50, v51 offset1:1
	ds_write2_b32 v21, v52, v53 offset1:1
	s_waitcnt lgkmcnt(0)
	ds_read2_b32 v[24:25], v6 offset0:33 offset1:41
	ds_read2_b32 v[26:27], v6 offset1:8
	ds_read2_b32 v[28:29], v6 offset0:66 offset1:74
	ds_read2_b32 v[30:31], v6 offset0:99 offset1:107
	ds_read2_b32 v[32:33], v6 offset0:132 offset1:140
	ds_read2_b32 v[34:35], v6 offset0:165 offset1:173
	ds_read2_b32 v[36:37], v6 offset0:198 offset1:206
	ds_read2_b32 v[38:39], v6 offset0:231 offset1:239
	ds_read2_b32 v[40:41], v6 offset0:49 offset1:57
	ds_read2_b32 v[42:43], v6 offset0:16 offset1:24
	ds_read2_b32 v[44:45], v6 offset0:82 offset1:90
	ds_read2_b32 v[46:47], v6 offset0:115 offset1:123
	ds_read2_b32 v[48:49], v6 offset0:148 offset1:156
	ds_read2_b32 v[50:51], v6 offset0:181 offset1:189
	ds_read2_b32 v[52:53], v6 offset0:214 offset1:222
	ds_read2_b32 v[62:63], v6 offset0:247 offset1:255
	s_waitcnt lgkmcnt(14)
	v_cvt_pk_bf16_f32 v22, v26, v24
	s_waitcnt lgkmcnt(12)
	v_cvt_pk_bf16_f32 v23, v28, v30
	v_cvt_pk_bf16_f32 v26, v27, v25
	s_waitcnt lgkmcnt(10)
	v_cvt_pk_bf16_f32 v24, v32, v34
	s_waitcnt lgkmcnt(8)
	v_cvt_pk_bf16_f32 v25, v36, v38
	v_cvt_pk_bf16_f32 v27, v29, v31
	v_cvt_pk_bf16_f32 v28, v33, v35
	v_cvt_pk_bf16_f32 v29, v37, v39
	s_waitcnt lgkmcnt(6)
	v_cvt_pk_bf16_f32 v30, v42, v40
	s_waitcnt lgkmcnt(4)
	v_cvt_pk_bf16_f32 v31, v44, v46
	s_waitcnt lgkmcnt(2)
	v_cvt_pk_bf16_f32 v32, v48, v50
	s_waitcnt lgkmcnt(0)
	v_cvt_pk_bf16_f32 v33, v52, v62
	v_cvt_pk_bf16_f32 v34, v43, v41
	v_cvt_pk_bf16_f32 v35, v45, v47
	v_cvt_pk_bf16_f32 v36, v49, v51
	v_cvt_pk_bf16_f32 v37, v53, v63
	global_store_dwordx4 v[56:57], v[22:25], off
	global_store_dwordx4 v[58:59], v[26:29], off
	global_store_dwordx4 v[60:61], v[30:33], off
	global_store_dwordx4 v[54:55], v[34:37], off
	s_waitcnt lgkmcnt(0)
	s_cbranch_scc1 .LBB0_27
	s_mov_b32 s14, s51

; __device__ __forceinline__ unsigned pk2(float lo, float hi) { f32x2_t v = {lo, hi}; bf16x2_t b = __builtin_convertvector(v, bf16x2_t); return __builtin_bit_cast(unsigned, b); }
; __global__ void __launch_bounds__(NTHREADS, 2) fwd_megakernel(Args A) {
;     ...
;     for (int m = 2 * gw; m < MROWS; m += 2 * NGW) {
;         const f32x4* xr = (const f32x4*)(A.x + (size_t)m * DM) + 2 * lane; v4u* o16 = (v4u*)(XB + (size_t)m * DM) + lane; float s0 = 0.f, s1 = 0.f;
;         f32x4 va[4], vb[4];
; #pragma unroll
;         for (int j = 0; j < 2; ++j) { va[2 * j] = xr[128 * j]; va[2 * j + 1] = xr[128 * j + 1]; vb[2 * j] = xr[256 + 128 * j]; vb[2 * j + 1] = xr[256 + 128 * j + 1]; }
; #pragma unroll
;         for (int j = 0; j < 4; ++j) { s0 += (va[j][0] * va[j][0] + va[j][1] * va[j][1]) + (va[j][2] * va[j][2] + va[j][3] * va[j][3]); s1 += (vb[j][0] * vb[j][0] + vb[j][1] * vb[j][1]) + (vb[j][2] * vb[j][2] + vb[j][3] * vb[j][3]); }
; #pragma unroll
;         for (int j = 0; j < 2; ++j) {
;             o16[64 * j] = (v4u){pk2(va[2 * j][0], va[2 * j][1]), pk2(va[2 * j][2], va[2 * j][3]), pk2(va[2 * j + 1][0], va[2 * j + 1][1]), pk2(va[2 * j + 1][2], va[2 * j + 1][3])};
;             o16[128 + 64 * j] = (v4u){pk2(vb[2 * j][0], vb[2 * j][1]), pk2(vb[2 * j][2], vb[2 * j][3]), pk2(vb[2 * j + 1][0], vb[2 * j + 1][1]), pk2(vb[2 * j + 1][2], vb[2 * j + 1][3])};
;         }
; #pragma unroll
;         for (int o = 1; o < 64; o <<= 1) { s0 += __shfl_xor(s0, o); s1 += __shfl_xor(s1, o); }
;         if (lane == 0) { ssq[m] = s0; ssq[m + 1] = s1; }
;     }
.LBB0_32:
	v_add_co_u32_e32 v38, vcc, 0xfffff000, v6
	v_lshl_add_u64 v[42:43], v[6:7], 0, s[22:23]
	s_nop 0
	v_addc_co_u32_e32 v39, vcc, -1, v7, vcc
	s_waitcnt lgkmcnt(0)
	global_load_dwordx4 v[8:11], v[6:7], off offset:-2064 nt
	global_load_dwordx4 v[18:21], v[6:7], off offset:-16 nt
	global_load_dwordx4 v[22:25], v[6:7], off nt
	global_load_dwordx4 v[26:29], v[6:7], off offset:-2048 nt
	global_load_dwordx4 v[30:33], v[38:39], off offset:-16 nt
	global_load_dwordx4 v[34:37], v[6:7], off offset:-4096 nt
	s_nop 0
	global_load_dwordx4 v[38:41], v[38:39], off offset:-2064 nt
	s_waitcnt vmcnt(6)
	v_mov_b32_e32 v55, v11
	global_load_dwordx4 v[42:45], v[42:43], off offset:16 nt
	s_waitcnt vmcnt(6)
	v_cvt_pk_bf16_f32 v46, v18, v19
	v_cvt_pk_bf16_f32 v47, v20, v21
	s_waitcnt vmcnt(5)
	v_cvt_pk_bf16_f32 v48, v22, v23
	v_cvt_pk_bf16_f32 v49, v24, v25
	v_mov_b32_e32 v57, v18
	v_mov_b32_e32 v59, v20
	v_mov_b32_e32 v61, v22
	v_mov_b32_e32 v63, v24
	s_waitcnt vmcnt(4)
	v_mov_b32_e32 v67, v27
	v_mov_b32_e32 v71, v29
	v_mov_b32_e32 v73, v9
	s_waitcnt vmcnt(3)
	v_mov_b32_e32 v18, v31
	v_mov_b32_e32 v20, v33
	s_waitcnt vmcnt(2)
	v_mov_b32_e32 v22, v35
	v_mov_b32_e32 v24, v37
	s_waitcnt vmcnt(1)
	v_mov_b32_e32 v54, v41
	v_mov_b32_e32 v72, v39
	v_mov_b32_e32 v53, v10
	v_mov_b32_e32 v65, v26
	v_mov_b32_e32 v69, v28
	v_mov_b32_e32 v52, v40
	v_mov_b32_e32 v56, v30
	v_mov_b32_e32 v58, v32
	v_mov_b32_e32 v60, v34
	v_cvt_pk_bf16_f32 v50, v38, v39
	v_mov_b32_e32 v39, v8
	v_mov_b32_e32 v62, v36
	v_pk_mul_f32 v[18:19], v[18:19], v[18:19]
	v_pk_mul_f32 v[20:21], v[20:21], v[20:21]
	v_pk_mul_f32 v[22:23], v[22:23], v[22:23]
	v_pk_mul_f32 v[24:25], v[24:25], v[24:25]
	v_pk_mul_f32 v[54:55], v[54:55], v[54:55]
	v_pk_mul_f32 v[72:73], v[72:73], v[72:73]
	v_pk_fma_f32 v[52:53], v[52:53], v[52:53], v[54:55]
	v_pk_fma_f32 v[18:19], v[56:57], v[56:57], v[18:19]
	v_pk_fma_f32 v[20:21], v[58:59], v[58:59], v[20:21]
	v_pk_fma_f32 v[22:23], v[60:61], v[60:61], v[22:23]
	v_pk_fma_f32 v[24:25], v[62:63], v[62:63], v[24:25]
	v_pk_fma_f32 v[38:39], v[38:39], v[38:39], v[72:73]
	v_pk_add_f32 v[18:19], v[18:19], v[20:21]
	v_pk_add_f32 v[20:21], v[22:23], v[24:25]
	v_pk_add_f32 v[22:23], v[38:39], v[52:53]
	v_cvt_pk_bf16_f32 v8, v8, v9
	v_cvt_pk_bf16_f32 v9, v10, v11
	v_cvt_pk_bf16_f32 v10, v26, v27
	v_cvt_pk_bf16_f32 v11, v28, v29
	v_cvt_pk_bf16_f32 v51, v40, v41
	s_waitcnt vmcnt(0)
	v_mov_b32_e32 v66, v43
	v_mov_b32_e32 v70, v45
	v_mov_b32_e32 v64, v42
	v_mov_b32_e32 v68, v44
	v_pk_mul_f32 v[66:67], v[66:67], v[66:67]
	v_pk_mul_f32 v[70:71], v[70:71], v[70:71]
	v_pk_fma_f32 v[54:55], v[64:65], v[64:65], v[66:67]
	v_pk_fma_f32 v[64:65], v[68:69], v[68:69], v[70:71]
	v_cvt_pk_bf16_f32 v52, v42, v43
	v_pk_add_f32 v[54:55], v[54:55], v[64:65]
	v_cvt_pk_bf16_f32 v53, v44, v45
	v_pk_add_f32 v[22:23], v[22:23], v[54:55]
	s_nop 0
	v_pk_add_f32 v[18:19], v[22:23], v[18:19]
	v_lshl_add_u64 v[22:23], s[82:83], 0, v[2:3]
	v_pk_add_f32 v[18:19], v[18:19], v[20:21]
	ds_bpermute_b32 v20, v1, v18
	ds_bpermute_b32 v21, v1, v19
	v_add_co_u32_e32 v22, vcc, s11, v22
	s_waitcnt lgkmcnt(0)
	v_pk_add_f32 v[18:19], v[18:19], v[20:21]
	ds_bpermute_b32 v20, v13, v18
	ds_bpermute_b32 v21, v13, v19
	v_addc_co_u32_e32 v23, vcc, 0, v23, vcc
	global_store_dwordx4 v[22:23], v[8:11], off offset:2048
	global_store_dwordx4 v[22:23], v[50:53], off
	s_waitcnt lgkmcnt(0)
	v_pk_add_f32 v[18:19], v[18:19], v[20:21]
	ds_bpermute_b32 v20, v14, v18
	ds_bpermute_b32 v21, v14, v19
	s_waitcnt lgkmcnt(0)
	v_pk_add_f32 v[18:19], v[18:19], v[20:21]
	ds_bpermute_b32 v20, v15, v18
	ds_bpermute_b32 v21, v15, v19
	s_waitcnt lgkmcnt(0)
	v_pk_add_f32 v[8:9], v[18:19], v[20:21]
	ds_bpermute_b32 v10, v16, v8
	ds_bpermute_b32 v11, v16, v9
	v_cvt_pk_bf16_f32 v18, v30, v31
	v_cvt_pk_bf16_f32 v19, v32, v33
	v_cvt_pk_bf16_f32 v20, v34, v35
	v_cvt_pk_bf16_f32 v21, v36, v37
	s_waitcnt lgkmcnt(0)
	v_pk_add_f32 v[8:9], v[8:9], v[10:11]
	ds_bpermute_b32 v10, v17, v8
	ds_bpermute_b32 v11, v17, v9
	global_store_dwordx4 v[22:23], v[18:21], off offset:1024
	global_store_dwordx4 v[22:23], v[46:49], off offset:3072
	s_and_saveexec_b64 s[24:25], s[4:5]
	s_cbranch_execz .LBB0_31
	s_add_u32 s26, s82, s14
	s_addc_u32 s27, s83, s15
	s_waitcnt lgkmcnt(0)
	v_pk_add_f32 v[8:9], v[8:9], v[10:11]
	global_store_dwordx2 v5, v[8:9], s[26:27]
	s_branch .LBB0_31
